# attention: 64-bit K/V pointer increments moved out of the MFMA stream in both main loops
# baseline (speedup 1.0000x reference)
.LBB0_813:
	ds_read_b128 v[98:101], v201 offset:13312
	ds_read_b128 v[102:105], v201 offset:13344
	v_add_u32_e32 v206, 0x6800, v179
	v_exp_f32_e32 v50, v50
	v_exp_f32_e32 v51, v51
	s_waitcnt lgkmcnt(1)
	v_mfma_f32_32x32x16_bf16 v[82:97], v[98:101], v[114:117], v[34:49]
	v_exp_f32_e32 v52, v52
	v_exp_f32_e32 v53, v53
	v_exp_f32_e32 v54, v54
	v_exp_f32_e32 v55, v55
	v_exp_f32_e32 v56, v56
	v_exp_f32_e32 v57, v57
	v_add_u32_e32 v207, 0x7800, v179
	s_waitcnt lgkmcnt(0)
	v_mfma_f32_32x32x16_bf16 v[82:97], v[102:105], v[118:121], v[82:97]
	ds_read_b128 v[98:101], v201 offset:13376
	ds_read_b128 v[102:105], v201 offset:13408
	v_exp_f32_e32 v58, v58
	v_exp_f32_e32 v59, v59
	v_exp_f32_e32 v60, v60
	v_exp_f32_e32 v61, v61
	v_exp_f32_e32 v62, v62
	v_exp_f32_e32 v63, v63
	s_waitcnt lgkmcnt(1)
	v_mfma_f32_32x32x16_bf16 v[82:97], v[98:101], v[122:125], v[82:97]
	v_exp_f32_e32 v64, v64
	v_exp_f32_e32 v65, v65
	v_exp_f32_e32 v66, v66
	v_exp_f32_e32 v67, v67
	v_exp_f32_e32 v68, v68
	v_exp_f32_e32 v69, v69
	v_exp_f32_e32 v70, v70
	s_waitcnt lgkmcnt(0)
	v_mfma_f32_32x32x16_bf16 v[82:97], v[102:105], v[126:129], v[82:97]
	ds_read_b128 v[98:101], v201 offset:13440
	ds_read_b128 v[102:105], v201 offset:13472
	ds_read_b128 v[170:173], v201 offset:19968
	ds_read_b128 v[174:177], v201 offset:20000
	v_exp_f32_e32 v71, v71
	v_exp_f32_e32 v72, v72
	v_exp_f32_e32 v73, v73
	v_exp_f32_e32 v74, v74
	v_exp_f32_e32 v75, v75
	s_waitcnt lgkmcnt(3)
	v_mfma_f32_32x32x16_bf16 v[82:97], v[98:101], v[130:133], v[82:97]
	v_exp_f32_e32 v76, v76
	v_exp_f32_e32 v77, v77
	v_exp_f32_e32 v78, v78
	v_exp_f32_e32 v79, v79
	v_exp_f32_e32 v80, v80
	v_exp_f32_e32 v81, v81
	s_waitcnt lgkmcnt(2)
	v_mfma_f32_32x32x16_bf16 v[82:97], v[102:105], v[134:137], v[82:97]
	s_waitcnt lgkmcnt(1)
	v_mfma_f32_32x32x16_bf16 v[98:113], v[170:173], v[114:117], v[34:49]
	s_waitcnt lgkmcnt(0)
	v_mfma_f32_32x32x16_bf16 v[98:113], v[174:177], v[118:121], v[98:113]
	ds_read_b128 v[170:173], v201 offset:20032
	ds_read_b128 v[174:177], v201 offset:20064
	s_waitcnt lgkmcnt(1)
	v_mfma_f32_32x32x16_bf16 v[98:113], v[170:173], v[122:125], v[98:113]
	s_waitcnt lgkmcnt(0)
	v_mfma_f32_32x32x16_bf16 v[98:113], v[174:177], v[126:129], v[98:113]
	ds_read_b128 v[170:173], v201 offset:20096
	ds_read_b128 v[174:177], v201 offset:20128
	ds_read2_b64 v[180:183], v206 offset0:4 offset1:6
	s_waitcnt lgkmcnt(2)
	v_mfma_f32_32x32x16_bf16 v[98:113], v[170:173], v[130:133], v[98:113]
	ds_read2_b64 v[170:173], v206 offset1:2
	s_waitcnt lgkmcnt(2)
	v_mfma_f32_32x32x16_bf16 v[98:113], v[174:177], v[134:137], v[98:113]
	v_cvt_pk_bf16_f32 v174, v50, v51
	v_cvt_pk_bf16_f32 v175, v52, v53
	v_cvt_pk_bf16_f32 v176, v54, v55
	v_cvt_pk_bf16_f32 v177, v56, v57
	s_waitcnt lgkmcnt(0)
	s_nop 0
	v_mfma_f32_32x32x16_bf16 v[2:17], v[170:173], v[174:177], v[2:17]
	ds_read2_b64 v[170:173], v207 offset0:32 offset1:34
	s_waitcnt lgkmcnt(0)
	v_mfma_f32_32x32x16_bf16 v[18:33], v[170:173], v[174:177], v[18:33]
	ds_read2_b64 v[174:177], v207 offset0:36 offset1:38
	v_cvt_pk_bf16_f32 v170, v58, v59
	v_cvt_pk_bf16_f32 v171, v60, v61
	v_cvt_pk_bf16_f32 v172, v62, v63
	v_cvt_pk_bf16_f32 v173, v64, v65
	s_nop 1
	v_mfma_f32_32x32x16_bf16 v[2:17], v[180:183], v[170:173], v[2:17]
	ds_read2_b64 v[180:183], v206 offset0:8 offset1:10
	s_waitcnt lgkmcnt(1)
	v_mfma_f32_32x32x16_bf16 v[18:33], v[174:177], v[170:173], v[18:33]
	ds_read2_b64 v[174:177], v207 offset0:40 offset1:42
	v_cvt_pk_bf16_f32 v170, v66, v67
	v_cvt_pk_bf16_f32 v171, v68, v69
	v_cvt_pk_bf16_f32 v172, v70, v71
	v_cvt_pk_bf16_f32 v173, v72, v73
	s_waitcnt lgkmcnt(1)
	s_nop 0
	v_mfma_f32_32x32x16_bf16 v[2:17], v[180:183], v[170:173], v[2:17]
	ds_read2_b64 v[180:183], v206 offset0:12 offset1:14
	s_waitcnt lgkmcnt(1)
	v_mfma_f32_32x32x16_bf16 v[18:33], v[174:177], v[170:173], v[18:33]
	ds_read2_b64 v[174:177], v207 offset0:44 offset1:46
	v_cvt_pk_bf16_f32 v170, v74, v75
	v_cvt_pk_bf16_f32 v171, v76, v77
	v_cvt_pk_bf16_f32 v172, v78, v79
	v_cvt_pk_bf16_f32 v173, v80, v81
	s_waitcnt vmcnt(1)
	ds_write_b128 v190, v[142:145]
	s_waitcnt lgkmcnt(2)
	v_mfma_f32_32x32x16_bf16 v[2:17], v[180:183], v[170:173], v[2:17]
	s_waitcnt lgkmcnt(1)
	v_mfma_f32_32x32x16_bf16 v[18:33], v[174:177], v[170:173], v[18:33]
	s_and_saveexec_b64 s[8:9], s[6:7]
	v_add_u32_e32 v142, v159, v191
	ds_write_b128 v142, v[138:141]
	s_or_b64 exec, exec, s[8:9]
	v_add_co_u32_e32 v142, vcc, 0xad74000, v168
	v_add3_u32 v208, v0, v158, s4
	s_nop 0
	v_addc_co_u32_e32 v143, vcc, 0, v169, vcc
	s_waitcnt vmcnt(0)
	ds_write2_b64 v208, v[146:147], v[148:149] offset1:1
	s_waitcnt lgkmcnt(0)
	s_barrier
	v_lshl_add_u64 v[150:151], v[150:151], 0, s[92:93]
	v_lshl_add_u64 v[152:153], v[152:153], 0, s[92:93]
	v_lshl_add_u64 v[160:161], v[160:161], 0, s[2:3]
	global_load_dwordx4 v[142:145], v[142:143], off
	s_and_saveexec_b64 s[8:9], s[6:7]
	s_cbranch_execz .LBB0_817
	v_add_co_u32_e32 v138, vcc, 0xad74000, v166
	s_nop 1
	v_addc_co_u32_e32 v139, vcc, 0, v167, vcc
	global_load_dwordx4 v[138:141], v[138:139], off

; #define AT_STEPM(C0, C1, MC, N0, N1, MN, t_) do { \
;         AT_WRITEK((t_) + 1); AT_WRITEV(t_); \
;         __syncthreads(); \
;         AT_LOADK((t_) + 2); AT_LOADV((t_) + 1); \
;         AT_SM1(C0, C1, MC, t_, 0); MN = mref; AT_QK(N0, N1, (t_) + 1); AT_SM2(C0, C1, t_); \
;     } while (0)
; DI void attn_unit(int wv, int h, int qb, const bf16_t* QB, const bf16_t* KB, const bf16_t* VT, bf16_t* MIX, LAS unsigned char* lds) {
;     ...
;         AT_STEPM(pA0, pA1, mA, pB0, pB1, mB, t);
;         AT_STEPM(pB0, pB1, mB, pA0, pA1, mA, t + 1);
.LBB0_820:
	ds_read_b128 v[66:69], v201
	ds_read_b128 v[70:73], v201 offset:32
	v_add_u32_e32 v209, 0x8800, v179
	v_exp_f32_e32 v163, v86
	v_exp_f32_e32 v162, v87
	s_waitcnt lgkmcnt(1)
	v_mfma_f32_32x32x16_bf16 v[50:65], v[66:69], v[114:117], v[34:49]
	v_exp_f32_e32 v82, v82
	v_exp_f32_e32 v83, v83
	v_exp_f32_e32 v84, v84
	v_exp_f32_e32 v85, v85
	v_exp_f32_e32 v87, v104
	v_exp_f32_e32 v86, v105
	s_waitcnt lgkmcnt(0)
	v_mfma_f32_32x32x16_bf16 v[50:65], v[70:73], v[118:121], v[50:65]
	ds_read_b128 v[66:69], v201 offset:64
	ds_read_b128 v[70:73], v201 offset:96
	v_exp_f32_e32 v175, v102
	v_exp_f32_e32 v174, v103
	v_cvt_pk_bf16_f32 v102, v82, v83
	v_cvt_pk_bf16_f32 v103, v84, v85
	v_cvt_pk_bf16_f32 v104, v163, v162
	v_exp_f32_e32 v177, v96
	s_waitcnt lgkmcnt(1)
	v_mfma_f32_32x32x16_bf16 v[50:65], v[66:69], v[122:125], v[50:65]
	ds_read_b128 v[66:69], v201 offset:128
	v_exp_f32_e32 v176, v97
	v_exp_f32_e32 v98, v98
	v_exp_f32_e32 v99, v99
	v_exp_f32_e32 v100, v100
	v_exp_f32_e32 v101, v101
	v_add_f32_e32 v181, v98, v82
	s_waitcnt lgkmcnt(1)
	v_mfma_f32_32x32x16_bf16 v[50:65], v[70:73], v[126:129], v[50:65]
	ds_read_b128 v[166:169], v201 offset:6656
	ds_read_b128 v[170:173], v201 offset:6688
	ds_read_b128 v[182:185], v201 offset:6720
	ds_read_b128 v[186:189], v201 offset:6752
	ds_read_b128 v[70:73], v201 offset:160
	ds_read_b128 v[210:213], v201 offset:6784
	ds_read_b128 v[214:217], v201 offset:6816
	v_add_f32_e32 v203, v99, v83
	v_add_f32_e32 v181, 0, v181
	v_add_f32_e32 v228, v100, v84
	v_add_f32_e32 v181, v203, v181
	v_add_f32_e32 v229, v101, v85
	s_waitcnt lgkmcnt(7)
	v_mfma_f32_32x32x16_bf16 v[50:65], v[66:69], v[130:133], v[50:65]
	v_add_f32_e64 v218, v174, v162
	v_add_f32_e64 v219, v175, v163
	s_add_i32 s12, s12, 2
	s_add_i32 s0, s90, 2
	s_add_i32 s1, s89, 2
	s_waitcnt lgkmcnt(2)
	v_mfma_f32_32x32x16_bf16 v[50:65], v[70:73], v[134:137], v[50:65]
	s_cmp_ge_u32 s12, s29
	v_mfma_f32_32x32x16_bf16 v[66:81], v[166:169], v[114:117], v[34:49]
	v_exp_f32_e32 v167, v88
	v_exp_f32_e32 v166, v89
	v_exp_f32_e32 v169, v90
	v_exp_f32_e32 v89, v106
	v_exp_f32_e32 v168, v91
	v_exp_f32_e32 v88, v107
	v_exp_f32_e32 v91, v108
	v_mfma_f32_32x32x16_bf16 v[66:81], v[170:173], v[118:121], v[66:81]
	v_exp_f32_e32 v90, v109
	ds_read2_b64 v[106:109], v209 offset0:64 offset1:66
	v_exp_f32_e32 v171, v92
	v_exp_f32_e32 v170, v93
	v_exp_f32_e32 v93, v110
	v_exp_f32_e32 v92, v111
	v_mfma_f32_32x32x16_bf16 v[66:81], v[182:185], v[122:125], v[66:81]
	v_cvt_pk_bf16_f32 v105, v167, v166
	v_exp_f32_e32 v173, v94
	v_exp_f32_e32 v172, v95
	v_exp_f32_e32 v95, v112
	v_exp_f32_e32 v94, v113
	ds_read2_b64 v[110:113], v209 offset0:68 offset1:70
	v_add_f32_e32 v220, v86, v166
	v_add_f32_e32 v221, v87, v167
	v_mfma_f32_32x32x16_bf16 v[66:81], v[186:189], v[126:129], v[66:81]
	v_add_f32_e32 v222, v88, v168
	v_add_f32_e32 v223, v89, v169
	v_add_f32_e32 v96, v90, v170
	v_add_f32_e32 v97, v91, v171
	v_add_f32_e32 v224, v92, v172
	v_add_f32_e32 v225, v93, v173
	v_add_f32_e32 v226, v94, v176
	v_add_f32_e32 v227, v95, v177
	s_waitcnt lgkmcnt(3)
	v_mfma_f32_32x32x16_bf16 v[66:81], v[210:213], v[130:133], v[66:81]
	v_add_u32_e32 v210, 0x9800, v179
	ds_read2_b64 v[182:185], v210 offset0:96 offset1:98
	s_nop 0
	v_cvt_pk_bf16_f32 v212, v89, v88
	s_waitcnt lgkmcnt(2)
	v_mfma_f32_32x32x16_bf16 v[2:17], v[106:109], v[102:105], v[2:17]
	v_cvt_pk_bf16_f32 v106, v169, v168
	v_cvt_pk_bf16_f32 v107, v171, v170
	v_cvt_pk_bf16_f32 v108, v173, v172
	v_cvt_pk_bf16_f32 v109, v177, v176
	s_waitcnt lgkmcnt(0)
	v_mfma_f32_32x32x16_bf16 v[18:33], v[182:185], v[102:105], v[18:33]
	ds_read2_b64 v[102:105], v210 offset0:100 offset1:102
	v_cvt_pk_bf16_f32 v184, v175, v174
	v_cvt_pk_bf16_f32 v185, v87, v86
	v_cvt_pk_bf16_f32 v182, v98, v99
	v_cvt_pk_bf16_f32 v183, v100, v101
	v_mfma_f32_32x32x16_bf16 v[2:17], v[110:113], v[106:109], v[2:17]
	ds_read2_b64 v[110:113], v209 offset0:72 offset1:74
	ds_read2_b64 v[186:189], v210 offset0:104 offset1:106
	s_waitcnt lgkmcnt(2)
	v_mfma_f32_32x32x16_bf16 v[18:33], v[102:105], v[106:109], v[18:33]
	s_waitcnt lgkmcnt(1)
	v_mfma_f32_32x32x16_bf16 v[2:17], v[110:113], v[182:185], v[2:17]
	v_add_f32_e32 v110, v228, v181
	v_add_f32_e32 v110, v229, v110
	v_add_f32_e32 v110, v219, v110
	v_add_f32_e32 v110, v218, v110
	v_add_f32_e32 v110, v221, v110
	v_add_f32_e32 v110, v220, v110
	v_add_f32_e32 v110, v223, v110
	s_waitcnt lgkmcnt(0)
	v_mfma_f32_32x32x16_bf16 v[18:33], v[186:189], v[182:185], v[18:33]
	v_add_f32_e32 v110, v222, v110
	v_add_f32_e32 v97, v97, v110
	v_add_f32_e32 v96, v96, v97
	v_add_f32_e32 v96, v225, v96
	v_add_f32_e32 v96, v224, v96
	v_add_f32_e32 v96, v227, v96
	v_add_f32_e32 v96, v226, v96
	v_mfma_f32_32x32x16_bf16 v[66:81], v[214:217], v[134:137], v[66:81]
	v_add_f32_e32 v203, v180, v96
	v_cvt_pk_bf16_f32 v213, v91, v90
	v_lshl_add_u64 v[96:97], v[156:157], 0, s[2:3]
	v_cvt_pk_bf16_f32 v214, v93, v92
	v_cvt_pk_bf16_f32 v215, v95, v94
	ds_read2_b64 v[102:105], v209 offset0:76 offset1:78
	ds_read2_b64 v[106:109], v210 offset0:108 offset1:110
	s_waitcnt lgkmcnt(1)
	v_mfma_f32_32x32x16_bf16 v[2:17], v[102:105], v[212:215], v[2:17]
	s_waitcnt lgkmcnt(0)
	v_mfma_f32_32x32x16_bf16 v[18:33], v[106:109], v[212:215], v[18:33]
	s_cbranch_scc0 .LBB0_800
	s_add_i32 s91, s29, 4
	s_mov_b64 s[8:9], -1
	s_cmp_lt_u32 s12, s91
	v_lshlrev_b32_e32 v158, 2, v178
	s_cbranch_scc1 .LBB0_823
	v_lshlrev_b32_e32 v0, 2, v178
	s_mov_b64 s[8:9], 0

.LBB0_873:
	s_or_b64 exec, exec, s[8:9]
	v_add_co_u32_e32 v2, vcc, s96, v10
	v_add_f32_e32 v4, v82, v66
	s_nop 0
	v_addc_co_u32_e32 v3, vcc, 0, v11, vcc
	global_load_dwordx4 v[160:163], v[2:3], off offset:256
	v_lshl_add_u64 v[178:179], v[178:179], 0, s[92:93]
	v_lshl_add_u64 v[180:181], v[180:181], 0, s[92:93]
	v_lshl_add_u64 v[182:183], v[182:183], 0, s[2:3]
	v_add_f32_e32 v2, v80, v64
	v_add_f32_e32 v3, v81, v65
	v_add_f32_e32 v2, 0, v2
	v_add_f32_e32 v2, v3, v2
	v_add_f32_e32 v5, v83, v67
	v_add_f32_e32 v2, v4, v2
	v_add_f32_e32 v6, v84, v68
	v_add_f32_e32 v2, v5, v2
	v_max_f32_e32 v3, v97, v97
	v_max_f32_e32 v4, v96, v96
	v_add_f32_e32 v7, v85, v69
	v_add_f32_e32 v2, v6, v2
	v_max_f32_e32 v3, v4, v3
	v_add_f32_e32 v8, v86, v70
	v_add_f32_e32 v2, v7, v2
	v_max3_f32 v4, v98, v99, v113
	v_max3_f32 v3, v3, v112, v114
	v_add_f32_e32 v9, v87, v71
	v_add_f32_e32 v2, v8, v2
	v_max3_f32 v3, v3, v115, v100
	v_max3_f32 v4, v4, v102, v103
	v_add_f32_e32 v10, v88, v72
	v_add_f32_e32 v2, v9, v2
	v_max3_f32 v3, v3, v101, v116
	v_max3_f32 v4, v4, v118, v119
	v_add_f32_e32 v11, v89, v73
	v_add_f32_e32 v2, v10, v2
	v_max3_f32 v3, v3, v117, v104
	v_max3_f32 v4, v4, v106, v107
	v_add_f32_e32 v12, v90, v74
	v_add_f32_e32 v2, v11, v2
	v_max3_f32 v3, v3, v105, v120
	v_max3_f32 v4, v4, v122, v123
	v_add_f32_e32 v13, v91, v75
	v_add_f32_e32 v2, v12, v2
	v_max3_f32 v3, v3, v121, v108
	v_max3_f32 v4, v4, v110, v111
	v_add_f32_e32 v14, v92, v76
	v_add_f32_e32 v2, v13, v2
	v_max3_f32 v3, v3, v109, v124
	v_max3_f32 v4, v4, v126, v127
	v_add_f32_e32 v15, v93, v77
	v_add_f32_e32 v2, v14, v2
	v_max3_f32 v3, v3, v125, v4
	v_add_f32_e32 v64, v94, v78
	v_add_f32_e32 v2, v15, v2
	v_mov_b32_e32 v4, v3
	v_add_f32_e32 v65, v95, v79
	v_add_f32_e32 v2, v64, v2
	v_permlane32_swap_b32_e32 v3, v4
	v_add_f32_e32 v2, v65, v2
	v_max_f32_e32 v4, v4, v4
	v_max_f32_e32 v3, v3, v3
	v_add_f32_e32 v188, v208, v2
	v_sub_f32_e32 v2, v209, v209
	v_max_f32_e32 v3, v3, v4
	v_sub_f32_e32 v3, v3, v2
	v_cmp_lt_f32_e32 vcc, s97, v3
	v_cmp_neq_f32_e64 s[8:9], 0, v2
	s_or_b64 vcc, s[8:9], vcc
	s_cbranch_vccz .LBB0_893
	v_max_f32_e32 v3, v3, v3
	v_max_f32_e32 v3, 0, v3
	v_exp_f32_e64 v4, -v3
	v_add_f32_e32 v210, v209, v3
	v_add_f32_e32 v2, v2, v3
	v_xor_b32_e32 v48, 0x80000000, v210
	v_pk_add_f32 v[96:97], v[96:97], v[2:3] op_sel_hi:[1,0] neg_lo:[0,1] neg_hi:[0,1]
	v_pk_add_f32 v[112:113], v[112:113], v[2:3] op_sel_hi:[1,0] neg_lo:[0,1] neg_hi:[0,1]
	v_pk_add_f32 v[98:99], v[98:99], v[2:3] op_sel_hi:[1,0] neg_lo:[0,1] neg_hi:[0,1]
	v_pk_add_f32 v[114:115], v[114:115], v[2:3] op_sel_hi:[1,0] neg_lo:[0,1] neg_hi:[0,1]
	v_pk_add_f32 v[100:101], v[100:101], v[2:3] op_sel_hi:[1,0] neg_lo:[0,1] neg_hi:[0,1]
	v_pk_add_f32 v[116:117], v[116:117], v[2:3] op_sel_hi:[1,0] neg_lo:[0,1] neg_hi:[0,1]
	v_pk_add_f32 v[102:103], v[102:103], v[2:3] op_sel_hi:[1,0] neg_lo:[0,1] neg_hi:[0,1]
	v_pk_add_f32 v[118:119], v[118:119], v[2:3] op_sel_hi:[1,0] neg_lo:[0,1] neg_hi:[0,1]
	v_pk_add_f32 v[104:105], v[104:105], v[2:3] op_sel_hi:[1,0] neg_lo:[0,1] neg_hi:[0,1]
	v_pk_add_f32 v[120:121], v[120:121], v[2:3] op_sel_hi:[1,0] neg_lo:[0,1] neg_hi:[0,1]
	v_pk_add_f32 v[106:107], v[106:107], v[2:3] op_sel_hi:[1,0] neg_lo:[0,1] neg_hi:[0,1]
	v_pk_add_f32 v[122:123], v[122:123], v[2:3] op_sel_hi:[1,0] neg_lo:[0,1] neg_hi:[0,1]
	v_pk_add_f32 v[108:109], v[108:109], v[2:3] op_sel_hi:[1,0] neg_lo:[0,1] neg_hi:[0,1]
	v_pk_add_f32 v[124:125], v[124:125], v[2:3] op_sel_hi:[1,0] neg_lo:[0,1] neg_hi:[0,1]
	v_pk_add_f32 v[110:111], v[110:111], v[2:3] op_sel_hi:[1,0] neg_lo:[0,1] neg_hi:[0,1]
	v_pk_add_f32 v[126:127], v[126:127], v[2:3] op_sel_hi:[1,0] neg_lo:[0,1] neg_hi:[0,1]
	v_pk_mul_f32 v[46:47], v[46:47], v[4:5] op_sel_hi:[1,0]
	v_pk_mul_f32 v[44:45], v[44:45], v[4:5] op_sel_hi:[1,0]
	v_pk_mul_f32 v[42:43], v[42:43], v[4:5] op_sel_hi:[1,0]
	v_pk_mul_f32 v[40:41], v[40:41], v[4:5] op_sel_hi:[1,0]
	v_pk_mul_f32 v[38:39], v[38:39], v[4:5] op_sel_hi:[1,0]
	v_pk_mul_f32 v[36:37], v[36:37], v[4:5] op_sel_hi:[1,0]
	v_pk_mul_f32 v[34:35], v[34:35], v[4:5] op_sel_hi:[1,0]
	v_pk_mul_f32 v[32:33], v[32:33], v[4:5] op_sel_hi:[1,0]
	v_pk_mul_f32 v[30:31], v[30:31], v[4:5] op_sel_hi:[1,0]
	v_pk_mul_f32 v[28:29], v[28:29], v[4:5] op_sel_hi:[1,0]
	v_pk_mul_f32 v[26:27], v[26:27], v[4:5] op_sel_hi:[1,0]
	v_pk_mul_f32 v[24:25], v[24:25], v[4:5] op_sel_hi:[1,0]
	v_pk_mul_f32 v[22:23], v[22:23], v[4:5] op_sel_hi:[1,0]
	v_pk_mul_f32 v[20:21], v[20:21], v[4:5] op_sel_hi:[1,0]
	v_pk_mul_f32 v[18:19], v[18:19], v[4:5] op_sel_hi:[1,0]
	v_pk_mul_f32 v[16:17], v[16:17], v[4:5] op_sel_hi:[1,0]
	v_mul_f32_e32 v188, v188, v4
	v_mov_b32_e32 v49, v48
	v_mov_b32_e32 v50, v48
	v_mov_b32_e32 v51, v48
	v_mov_b32_e32 v52, v48
	v_mov_b32_e32 v53, v48
	v_mov_b32_e32 v54, v48
	v_mov_b32_e32 v55, v48
	v_mov_b32_e32 v56, v48
	v_mov_b32_e32 v57, v48
	v_mov_b32_e32 v58, v48
	v_mov_b32_e32 v59, v48
	v_mov_b32_e32 v60, v48
	v_mov_b32_e32 v61, v48
	v_mov_b32_e32 v62, v48
	v_mov_b32_e32 v63, v48
.LBB0_875:
	ds_read_b128 v[2:5], v203
	ds_read_b128 v[6:9], v203 offset:32
	v_exp_f32_e32 v11, v100
	v_exp_f32_e32 v10, v101
	v_exp_f32_e32 v96, v96
	s_waitcnt lgkmcnt(1)
	v_mfma_f32_32x32x16_bf16 v[64:79], v[2:5], v[128:131], v[48:63]
	v_exp_f32_e32 v97, v97
	v_exp_f32_e32 v98, v98
	v_exp_f32_e32 v99, v99
	v_exp_f32_e32 v185, v126
	v_exp_f32_e32 v184, v127
	v_cvt_pk_bf16_f32 v100, v96, v97
	v_cvt_pk_bf16_f32 v101, v98, v99
	s_waitcnt lgkmcnt(0)
	v_mfma_f32_32x32x16_bf16 v[64:79], v[6:9], v[132:135], v[64:79]
	ds_read_b128 v[2:5], v203 offset:64
	ds_read_b128 v[6:9], v203 offset:96
	v_exp_f32_e32 v112, v112
	v_exp_f32_e32 v113, v113
	v_exp_f32_e32 v114, v114
	v_exp_f32_e32 v115, v115
	v_add_f32_e32 v189, v112, v96
	v_add_f32_e32 v208, v113, v97
	s_waitcnt lgkmcnt(1)
	v_mfma_f32_32x32x16_bf16 v[64:79], v[2:5], v[136:139], v[64:79]
	ds_read_b128 v[2:5], v203 offset:128
	v_add_f32_e32 v211, v114, v98
	v_add_f32_e32 v236, v115, v99
	s_add_i32 s76, s76, 2
	s_waitcnt lgkmcnt(1)
	v_mfma_f32_32x32x16_bf16 v[64:79], v[6:9], v[140:143], v[64:79]
	ds_read_b128 v[6:9], v203 offset:160
	s_cmp_ge_u32 s76, s15
	s_waitcnt lgkmcnt(1)
	v_mfma_f32_32x32x16_bf16 v[64:79], v[2:5], v[144:147], v[64:79]
	ds_read_b128 v[2:5], v203 offset:6656
	ds_read_b128 v[12:15], v203 offset:6688
	ds_read_b128 v[212:215], v203 offset:6720
	ds_read_b128 v[216:219], v203 offset:6752
	ds_read_b128 v[220:223], v203 offset:6784
	ds_read_b128 v[224:227], v203 offset:6816
	s_waitcnt lgkmcnt(5)
	v_mfma_f32_32x32x16_bf16 v[80:95], v[2:5], v[128:131], v[48:63]
	v_exp_f32_e32 v3, v116
	v_exp_f32_e32 v2, v117
	v_exp_f32_e32 v5, v118
	v_exp_f32_e32 v4, v119
	v_exp_f32_e32 v117, v104
	v_exp_f32_e32 v116, v105
	v_exp_f32_e32 v119, v106
	s_waitcnt lgkmcnt(4)
	v_mfma_f32_32x32x16_bf16 v[80:95], v[12:15], v[132:135], v[80:95]
	v_exp_f32_e32 v15, v102
	v_exp_f32_e32 v14, v103
	v_exp_f32_e32 v118, v107
	v_cvt_pk_bf16_f32 v102, v11, v10
	v_exp_f32_e32 v13, v124
	v_exp_f32_e32 v12, v125
	s_waitcnt lgkmcnt(3)
	v_mfma_f32_32x32x16_bf16 v[80:95], v[212:215], v[136:139], v[80:95]
	v_cvt_pk_bf16_f32 v124, v117, v116
	v_cvt_pk_bf16_f32 v125, v119, v118
	v_add_f32_e32 v190, v2, v10
	v_add_f32_e32 v191, v3, v11
	v_add_f32_e32 v228, v4, v14
	v_add_f32_e32 v229, v5, v15
	s_waitcnt lgkmcnt(2)
	v_mfma_f32_32x32x16_bf16 v[80:95], v[216:219], v[140:143], v[80:95]
	v_mfma_f32_32x32x16_bf16 v[64:79], v[6:9], v[148:151], v[64:79]
	v_exp_f32_e32 v7, v120
	v_exp_f32_e32 v6, v121
	v_exp_f32_e32 v121, v108
	v_exp_f32_e32 v120, v109
	v_exp_f32_e32 v9, v122
	v_exp_f32_e32 v8, v123
	s_waitcnt lgkmcnt(1)
	v_mfma_f32_32x32x16_bf16 v[80:95], v[220:223], v[144:147], v[80:95]
	v_add_u32_e32 v222, 0x8800, v0
	v_add_u32_e32 v0, 0x9800, v0
	v_exp_f32_e32 v123, v110
	v_exp_f32_e32 v122, v111
	ds_read2_b64 v[104:107], v222 offset0:64 offset1:66
	v_cvt_pk_bf16_f32 v103, v15, v14
	ds_read2_b64 v[108:111], v0 offset0:96 offset1:98
	s_waitcnt lgkmcnt(1)
	v_mfma_f32_32x32x16_bf16 v[32:47], v[104:107], v[100:103], v[32:47]
	ds_read2_b64 v[104:107], v222 offset0:68 offset1:70
	v_cvt_pk_bf16_f32 v126, v121, v120
	v_add_f32_e32 v230, v6, v116
	v_add_f32_e32 v231, v7, v117
	v_cvt_pk_bf16_f32 v216, v7, v6
	v_add_f32_e32 v232, v8, v118
	v_add_f32_e32 v233, v9, v119
	v_add_f32_e32 v234, v12, v120
	v_add_f32_e32 v235, v13, v121
	s_waitcnt lgkmcnt(1)
	v_mfma_f32_32x32x16_bf16 v[16:31], v[108:111], v[100:103], v[16:31]
	v_cvt_pk_bf16_f32 v127, v123, v122
	ds_read2_b64 v[100:103], v0 offset0:100 offset1:102
	v_cvt_pk_bf16_f32 v110, v3, v2
	v_cvt_pk_bf16_f32 v108, v112, v113
	v_cvt_pk_bf16_f32 v109, v114, v115
	s_waitcnt lgkmcnt(1)
	v_mfma_f32_32x32x16_bf16 v[32:47], v[104:107], v[124:127], v[32:47]
	v_add_f32_e32 v220, v184, v122
	v_add_f32_e32 v221, v185, v123
	v_cvt_pk_bf16_f32 v111, v5, v4
	ds_read2_b64 v[104:107], v222 offset0:72 offset1:74
	ds_read2_b64 v[212:215], v0 offset0:104 offset1:106
	s_waitcnt lgkmcnt(2)
	v_mfma_f32_32x32x16_bf16 v[16:31], v[100:103], v[124:127], v[16:31]
	s_nop 0
	v_cvt_pk_bf16_f32 v217, v9, v8
	s_nop 0
	v_cvt_pk_bf16_f32 v218, v13, v12
	s_waitcnt lgkmcnt(1)
	v_mfma_f32_32x32x16_bf16 v[32:47], v[104:107], v[108:111], v[32:47]
	v_cvt_pk_bf16_f32 v219, v185, v184
	ds_read2_b64 v[100:103], v222 offset0:76 offset1:78
	ds_read2_b64 v[104:107], v0 offset0:108 offset1:110
	v_add_f32_e32 v0, 0, v189
	v_add_f32_e32 v0, v208, v0
	v_add_f32_e32 v0, v211, v0
	v_add_f32_e32 v0, v236, v0
	s_waitcnt lgkmcnt(2)
	v_mfma_f32_32x32x16_bf16 v[16:31], v[212:215], v[108:111], v[16:31]
	v_add_f32_e32 v0, v191, v0
	v_add_f32_e32 v0, v190, v0
	v_add_f32_e32 v0, v229, v0
	v_add_f32_e32 v0, v228, v0
	v_add_f32_e32 v0, v231, v0
	v_add_f32_e32 v0, v230, v0
	v_add_f32_e32 v0, v233, v0
	v_mfma_f32_32x32x16_bf16 v[80:95], v[224:227], v[148:151], v[80:95]
	v_add_f32_e32 v0, v232, v0
	v_add_f32_e32 v0, v235, v0
	v_add_f32_e32 v0, v234, v0
	v_add_f32_e32 v0, v221, v0
	v_add_f32_e32 v0, v220, v0
	v_add_f32_e32 v208, v188, v0
	s_waitcnt lgkmcnt(1)
	v_mfma_f32_32x32x16_bf16 v[32:47], v[100:103], v[216:219], v[32:47]
	s_waitcnt lgkmcnt(0)
	v_mfma_f32_32x32x16_bf16 v[16:31], v[104:107], v[216:219], v[16:31]
	s_cbranch_scc1 .LBB0_894
